# stack26: SSD intra-chunk loop tail reads its four XT fragment pairs up front behind counted lgkmcnt waits (on top of stack24)
# speedup vs baseline: 1.0067x; 1.0067x over previous
; DI unsigned pk2(float lo, float hi) { return pg8::cvt_pk_bf16(lo, hi); }
; #define MFMA32(a, b, c) __builtin_amdgcn_mfma_f32_32x32x16_bf16((a), (b), (c), 0, 0, 0)
; DI void ssd_out_unit(const Params& P, int layer, int b, int c, char* lds, int tid) {
;     ...
;             for (int s2 = 0; s2 < 2; ++s2) {
;                 u32x4 pw0, pw1;
;                 pw0.x = pk2(X0[8 * s2], X0[8 * s2 + 1]); pw0.y = pk2(X0[8 * s2 + 2], X0[8 * s2 + 3]); pw0.z = pk2(X0[8 * s2 + 4], X0[8 * s2 + 5]); pw0.w = pk2(X0[8 * s2 + 6], X0[8 * s2 + 7]);
;                 pw1.x = pk2(X1[8 * s2], X1[8 * s2 + 1]); pw1.y = pk2(X1[8 * s2 + 2], X1[8 * s2 + 3]); pw1.z = pk2(X1[8 * s2 + 4], X1[8 * s2 + 5]); pw1.w = pk2(X1[8 * s2 + 6], X1[8 * s2 + 7]);
;                 const int xo = (32 * pb + r) * SP + 32 * sbk + 16 * s2 + 4 * hh;
;                 const u32x2 lo0 = *(const u32x2*)(XT[0] + xo), hi0 = *(const u32x2*)(XT[0] + xo + 8), lo1 = *(const u32x2*)(XT[1] + xo), hi1 = *(const u32x2*)(XT[1] + xo + 8);
;                 u32x4 v0; v0.x = lo0.x; v0.y = lo0.y; v0.z = hi0.x; v0.w = hi0.y; u32x4 v1; v1.x = lo1.x; v1.y = lo1.y; v1.z = hi1.x; v1.w = hi1.y;
;                 y0 = MFMA32(__builtin_bit_cast(bf16x8, pw0), __builtin_bit_cast(bf16x8, v0), y0);
;                 y1 = MFMA32(__builtin_bit_cast(bf16x8, pw1), __builtin_bit_cast(bf16x8, v1), y1); }
.LBB0_371:
	v_add_u32_e32 v49, 0, v137
	v_add_u32_e32 v236, 0x11000, v49
	ds_read_b64 v[216:217], v236
	ds_read_b64 v[218:219], v236 offset:16
	ds_read_b64 v[224:225], v236 offset:32
	ds_read_b64 v[226:227], v236 offset:48
	v_add_u32_e32 v236, 0x15400, v49
	ds_read_b64 v[220:221], v236
	ds_read_b64 v[222:223], v236 offset:16
	ds_read_b64 v[228:229], v236 offset:32
	ds_read_b64 v[230:231], v236 offset:48
	v_cvt_pk_bf16_f32 v212, v142, v141
	v_cvt_pk_bf16_f32 v213, v175, v176
	v_cvt_pk_bf16_f32 v214, v177, v190
	v_cvt_pk_bf16_f32 v215, v191, v192
	v_cvt_pk_bf16_f32 v34, v174, v34
	v_cvt_pk_bf16_f32 v35, v35, v36
	v_cvt_pk_bf16_f32 v36, v37, v38
	v_cvt_pk_bf16_f32 v37, v39, v193
	s_waitcnt lgkmcnt(6)
	v_mfma_f32_32x32x16_bf16 v[2:17], v[212:215], v[216:219], v[2:17]
	v_add_u32_e32 v140, -1, v140
	v_cmp_eq_u32_e32 vcc, 0, v140
	v_add_u32_e32 v139, 0x2200, v139
	v_add_u32_e32 v138, 32, v138
	v_add_u32_e32 v137, 64, v137
	s_waitcnt lgkmcnt(2)
	v_mfma_f32_32x32x16_bf16 v[18:33], v[34:37], v[220:223], v[18:33]
	v_cvt_pk_bf16_f32 v34, v40, v194
	v_cvt_pk_bf16_f32 v35, v195, v196
	v_cvt_pk_bf16_f32 v36, v197, v198
	v_cvt_pk_bf16_f32 v37, v199, v200
	v_cvt_pk_bf16_f32 v38, v41, v42
	v_cvt_pk_bf16_f32 v39, v43, v44
	v_cvt_pk_bf16_f32 v40, v45, v46
	v_cvt_pk_bf16_f32 v41, v47, v48
	s_waitcnt lgkmcnt(2)
	v_mfma_f32_32x32x16_bf16 v[2:17], v[34:37], v[224:227], v[2:17]
	s_or_b64 s[58:59], vcc, s[58:59]
	v_add_u32_e32 v136, 0x80, v136
	s_waitcnt lgkmcnt(0)
	v_mfma_f32_32x32x16_bf16 v[18:33], v[38:41], v[228:231], v[18:33]
	s_andn2_b64 exec, exec, s[58:59]
	s_cbranch_execz .LBB0_367
